# WO / FF2 residual epilogues: four row groups of residual loads in flight (was two), vmcnt values from the simulated in-order queue
# baseline (speedup 1.0000x reference)
.LBB0_1563:
	s_lshl_b64 s[6:7], s[6:7], 12
	s_add_u32 s36, s36, s6
	s_addc_u32 s37, s37, s7
	s_waitcnt lgkmcnt(0)
	s_add_u32 s6, s44, s6
	s_addc_u32 s7, s45, s7
	s_lshl_b64 s[40:41], s[40:41], 2
	v_readlane_b32 s44, v255, 25
	v_readlane_b32 s45, v255, 26
	s_add_u32 s40, s44, s40
	s_addc_u32 s41, s45, s41
	v_lshrrev_b32_e32 v131, 1, v130
	s_lshl_b32 s44, s58, 8
	v_and_or_b32 v131, v131, 24, s44
	v_or_b32_e32 v150, s53, v131
	s_add_i32 s17, s17, s52
	v_ashrrev_i32_e32 v151, 31, v150
	v_and_or_b32 v152, v130, 15, s17
	v_lshl_add_u64 v[130:131], v[150:151], 2, s[40:41]
	s_movk_i32 s17, 0x2000
	v_add_co_u32_e32 v132, vcc, s17, v130
	v_ashrrev_i32_e32 v153, 31, v152
	s_nop 0
	v_addc_co_u32_e32 v133, vcc, 0, v131, vcc
	global_load_dwordx4 v[138:141], v[132:133], off
	v_lshlrev_b64 v[132:133], 10, v[152:153]
	v_lshl_add_u64 v[132:133], v[132:133], 0, v[150:151]
	v_lshlrev_b64 v[172:173], 2, v[132:133]
	v_lshl_add_u64 v[154:155], s[36:37], 0, v[172:173]
	v_lshl_add_u64 v[130:131], v[130:131], 0, s[0:1]
	v_lshl_add_u64 v[156:157], s[6:7], 0, v[172:173]
	global_load_dwordx4 v[142:145], v[130:131], off offset:16
	global_load_dwordx4 v[134:137], v[130:131], off offset:512
	s_nop 0
	global_load_dwordx4 v[130:133], v[130:131], off offset:528
	s_mov_b64 s[40:41], 0x80000
	s_and_b64 vcc, exec, s[42:43]
	v_add_u32_e32 v173, 0x0, v172
	global_load_dwordx4 v[146:149], v173, s[36:37]
	global_load_dwordx4 v[154:157], v173, s[36:37] offset:16
	global_load_dwordx4 v[158:161], v173, s[36:37] offset:512
	global_load_dwordx4 v[176:179], v173, s[36:37] offset:528
	v_add_u32_e32 v173, 0x10000, v172
	global_load_dwordx4 v[180:183], v173, s[36:37]
	global_load_dwordx4 v[184:187], v173, s[36:37] offset:16
	global_load_dwordx4 v[188:191], v173, s[36:37] offset:512
	global_load_dwordx4 v[202:205], v173, s[36:37] offset:528
	v_add_u32_e32 v173, 0x20000, v172
	global_load_dwordx4 v[206:209], v173, s[36:37]
	global_load_dwordx4 v[210:213], v173, s[36:37] offset:16
	global_load_dwordx4 v[214:217], v173, s[36:37] offset:512
	global_load_dwordx4 v[218:221], v173, s[36:37] offset:528
	v_add_u32_e32 v173, 0x30000, v172
	global_load_dwordx4 v[222:225], v173, s[36:37]
	global_load_dwordx4 v[226:229], v173, s[36:37] offset:16
	global_load_dwordx4 v[230:233], v173, s[36:37] offset:512
	global_load_dwordx4 v[234:237], v173, s[36:37] offset:528
	s_waitcnt vmcnt(12) lgkmcnt(0)
	v_pk_fma_f32 v[126:127], v[126:127], v[138:139], v[146:147]
	v_pk_fma_f32 v[128:129], v[128:129], v[140:141], v[148:149]
	v_pk_fma_f32 v[122:123], v[122:123], v[142:143], v[154:155]
	v_pk_fma_f32 v[124:125], v[124:125], v[144:145], v[156:157]
	v_pk_fma_f32 v[118:119], v[118:119], v[134:135], v[158:159]
	v_pk_fma_f32 v[120:121], v[120:121], v[136:137], v[160:161]
	v_pk_fma_f32 v[104:105], v[104:105], v[130:131], v[176:177]
	v_pk_fma_f32 v[106:107], v[106:107], v[132:133], v[178:179]
	v_add_u32_e32 v173, 0x80000, v172
	global_load_dwordx4 v[146:149], v173, s[36:37]
	global_load_dwordx4 v[154:157], v173, s[36:37] offset:16
	global_load_dwordx4 v[158:161], v173, s[36:37] offset:512
	global_load_dwordx4 v[176:179], v173, s[36:37] offset:528
	v_add_u32_e32 v150, 0x0, v172
	global_store_dwordx4 v150, v[126:129], s[6:7]
	global_store_dwordx4 v150, v[122:125], s[6:7] offset:16
	global_store_dwordx4 v150, v[118:121], s[6:7] offset:512
	global_store_dwordx4 v150, v[104:107], s[6:7] offset:528
	s_waitcnt vmcnt(16)
	v_pk_fma_f32 v[114:115], v[114:115], v[138:139], v[180:181]
	v_pk_fma_f32 v[116:117], v[116:117], v[140:141], v[182:183]
	v_pk_fma_f32 v[108:109], v[108:109], v[142:143], v[184:185]
	v_pk_fma_f32 v[110:111], v[110:111], v[144:145], v[186:187]
	v_pk_fma_f32 v[100:101], v[100:101], v[134:135], v[188:189]
	v_pk_fma_f32 v[102:103], v[102:103], v[136:137], v[190:191]
	v_pk_fma_f32 v[88:89], v[88:89], v[130:131], v[202:203]
	v_pk_fma_f32 v[90:91], v[90:91], v[132:133], v[204:205]
	v_add_u32_e32 v173, 0x90000, v172
	global_load_dwordx4 v[180:183], v173, s[36:37]
	global_load_dwordx4 v[184:187], v173, s[36:37] offset:16
	global_load_dwordx4 v[188:191], v173, s[36:37] offset:512
	global_load_dwordx4 v[202:205], v173, s[36:37] offset:528
	v_add_u32_e32 v150, 0x10000, v172
	global_store_dwordx4 v150, v[114:117], s[6:7]
	global_store_dwordx4 v150, v[108:111], s[6:7] offset:16
	global_store_dwordx4 v150, v[100:103], s[6:7] offset:512
	global_store_dwordx4 v150, v[88:91], s[6:7] offset:528
	s_waitcnt vmcnt(20)
	v_pk_fma_f32 v[96:97], v[96:97], v[138:139], v[206:207]
	v_pk_fma_f32 v[98:99], v[98:99], v[140:141], v[208:209]
	v_pk_fma_f32 v[92:93], v[92:93], v[142:143], v[210:211]
	v_pk_fma_f32 v[94:95], v[94:95], v[144:145], v[212:213]
	v_pk_fma_f32 v[84:85], v[84:85], v[134:135], v[214:215]
	v_pk_fma_f32 v[86:87], v[86:87], v[136:137], v[216:217]
	v_pk_fma_f32 v[72:73], v[72:73], v[130:131], v[218:219]
	v_pk_fma_f32 v[74:75], v[74:75], v[132:133], v[220:221]
	v_add_u32_e32 v173, 0xa0000, v172
	global_load_dwordx4 v[206:209], v173, s[36:37]
	global_load_dwordx4 v[210:213], v173, s[36:37] offset:16
	global_load_dwordx4 v[214:217], v173, s[36:37] offset:512
	global_load_dwordx4 v[218:221], v173, s[36:37] offset:528
	v_add_u32_e32 v150, 0x20000, v172
	global_store_dwordx4 v150, v[96:99], s[6:7]
	global_store_dwordx4 v150, v[92:95], s[6:7] offset:16
	global_store_dwordx4 v150, v[84:87], s[6:7] offset:512
	global_store_dwordx4 v150, v[72:75], s[6:7] offset:528
	s_waitcnt vmcnt(24)
	v_pk_fma_f32 v[80:81], v[80:81], v[138:139], v[222:223]
	v_pk_fma_f32 v[82:83], v[82:83], v[140:141], v[224:225]
	v_pk_fma_f32 v[76:77], v[76:77], v[142:143], v[226:227]
	v_pk_fma_f32 v[78:79], v[78:79], v[144:145], v[228:229]
	v_pk_fma_f32 v[68:69], v[68:69], v[134:135], v[230:231]
	v_pk_fma_f32 v[70:71], v[70:71], v[136:137], v[232:233]
	v_pk_fma_f32 v[64:65], v[64:65], v[130:131], v[234:235]
	v_pk_fma_f32 v[66:67], v[66:67], v[132:133], v[236:237]
	v_add_u32_e32 v173, 0xb0000, v172
	global_load_dwordx4 v[222:225], v173, s[36:37]
	global_load_dwordx4 v[226:229], v173, s[36:37] offset:16
	global_load_dwordx4 v[230:233], v173, s[36:37] offset:512
	global_load_dwordx4 v[234:237], v173, s[36:37] offset:528
	v_add_u32_e32 v150, 0x30000, v172
	global_store_dwordx4 v150, v[80:83], s[6:7]
	global_store_dwordx4 v150, v[76:79], s[6:7] offset:16
	global_store_dwordx4 v150, v[68:71], s[6:7] offset:512
	global_store_dwordx4 v150, v[64:67], s[6:7] offset:528
	s_waitcnt vmcnt(28)
	v_pk_fma_f32 v[60:61], v[60:61], v[138:139], v[146:147]
	v_pk_fma_f32 v[62:63], v[62:63], v[140:141], v[148:149]
	v_pk_fma_f32 v[56:57], v[56:57], v[142:143], v[154:155]
	v_pk_fma_f32 v[58:59], v[58:59], v[144:145], v[156:157]
	v_pk_fma_f32 v[52:53], v[52:53], v[134:135], v[158:159]
	v_pk_fma_f32 v[54:55], v[54:55], v[136:137], v[160:161]
	v_pk_fma_f32 v[40:41], v[40:41], v[130:131], v[176:177]
	v_pk_fma_f32 v[42:43], v[42:43], v[132:133], v[178:179]
	v_add_u32_e32 v150, 0x80000, v172
	global_store_dwordx4 v150, v[60:63], s[6:7]
	global_store_dwordx4 v150, v[56:59], s[6:7] offset:16
	global_store_dwordx4 v150, v[52:55], s[6:7] offset:512
	global_store_dwordx4 v150, v[40:43], s[6:7] offset:528
	s_waitcnt vmcnt(24)
	v_pk_fma_f32 v[48:49], v[48:49], v[138:139], v[180:181]
	v_pk_fma_f32 v[50:51], v[50:51], v[140:141], v[182:183]
	v_pk_fma_f32 v[44:45], v[44:45], v[142:143], v[184:185]
	v_pk_fma_f32 v[46:47], v[46:47], v[144:145], v[186:187]
	v_pk_fma_f32 v[36:37], v[36:37], v[134:135], v[188:189]
	v_pk_fma_f32 v[38:39], v[38:39], v[136:137], v[190:191]
	v_pk_fma_f32 v[24:25], v[24:25], v[130:131], v[202:203]
	v_pk_fma_f32 v[26:27], v[26:27], v[132:133], v[204:205]
	v_add_u32_e32 v150, 0x90000, v172
	global_store_dwordx4 v150, v[48:51], s[6:7]
	global_store_dwordx4 v150, v[44:47], s[6:7] offset:16
	global_store_dwordx4 v150, v[36:39], s[6:7] offset:512
	global_store_dwordx4 v150, v[24:27], s[6:7] offset:528
	s_waitcnt vmcnt(20)
	v_pk_fma_f32 v[32:33], v[32:33], v[138:139], v[206:207]
	v_pk_fma_f32 v[34:35], v[34:35], v[140:141], v[208:209]
	v_pk_fma_f32 v[28:29], v[28:29], v[142:143], v[210:211]
	v_pk_fma_f32 v[30:31], v[30:31], v[144:145], v[212:213]
	v_pk_fma_f32 v[20:21], v[20:21], v[134:135], v[214:215]
	v_pk_fma_f32 v[22:23], v[22:23], v[136:137], v[216:217]
	v_pk_fma_f32 v[8:9], v[8:9], v[130:131], v[218:219]
	v_pk_fma_f32 v[10:11], v[10:11], v[132:133], v[220:221]
	v_add_u32_e32 v150, 0xa0000, v172
	global_store_dwordx4 v150, v[32:35], s[6:7]
	global_store_dwordx4 v150, v[28:31], s[6:7] offset:16
	global_store_dwordx4 v150, v[20:23], s[6:7] offset:512
	global_store_dwordx4 v150, v[8:11], s[6:7] offset:528
	s_waitcnt vmcnt(16)
	v_pk_fma_f32 v[16:17], v[16:17], v[138:139], v[222:223]
	v_pk_fma_f32 v[18:19], v[18:19], v[140:141], v[224:225]
	v_pk_fma_f32 v[12:13], v[12:13], v[142:143], v[226:227]
	v_pk_fma_f32 v[14:15], v[14:15], v[144:145], v[228:229]
	v_pk_fma_f32 v[4:5], v[4:5], v[134:135], v[230:231]
	v_pk_fma_f32 v[6:7], v[6:7], v[136:137], v[232:233]
	v_pk_fma_f32 v[0:1], v[0:1], v[130:131], v[234:235]
	v_pk_fma_f32 v[2:3], v[2:3], v[132:133], v[236:237]
	v_add_u32_e32 v150, 0xb0000, v172
	global_store_dwordx4 v150, v[16:19], s[6:7]
	global_store_dwordx4 v150, v[12:15], s[6:7] offset:16
	global_store_dwordx4 v150, v[4:7], s[6:7] offset:512
	global_store_dwordx4 v150, v[0:3], s[6:7] offset:528
	s_nop 1
	s_mov_b64 s[40:41], 0xb0000
	s_mov_b64 s[6:7], -1
	s_cbranch_vccnz .LBB0_1552
	s_andn2_b64 vcc, exec, s[10:11]
	s_cbranch_vccnz .LBB0_1551
	s_barrier
	s_branch .LBB0_1551

.LBB0_1763:
	s_lshl_b32 s15, s58, 8
	s_add_u32 s18, s38, s18
	s_addc_u32 s19, s39, s19
	s_lshl_b64 s[36:37], s[36:37], 2
	v_readlane_b32 s38, v255, 25
	v_readlane_b32 s39, v255, 26
	s_add_u32 s36, s38, s36
	s_addc_u32 s37, s39, s37
	v_lshrrev_b32_e32 v57, 1, v56
	s_lshl_b32 s17, s57, 8
	v_and_or_b32 v57, v57, 24, s17
	v_or_b32_e32 v58, s53, v57
	s_add_i32 s15, s15, s52
	v_and_or_b32 v176, v56, 15, s15
	v_ashrrev_i32_e32 v59, 31, v58
	v_lshlrev_b64 v[174:175], 2, v[58:59]
	v_ashrrev_i32_e32 v177, 31, v176
	v_lshl_add_u64 v[56:57], s[36:37], 0, v[174:175]
	s_mov_b64 s[36:37], 0x5000
	s_movk_i32 s15, 0x5000
	v_lshlrev_b64 v[146:147], 12, v[176:177]
	v_lshl_add_u64 v[58:59], v[56:57], 0, s[36:37]
	v_add_co_u32_e32 v56, vcc, s15, v56
	v_lshl_add_u64 v[146:147], s[18:19], 0, v[146:147]
	s_nop 0
	v_addc_co_u32_e32 v57, vcc, 0, v57, vcc
	v_lshl_add_u64 v[172:173], v[146:147], 0, v[174:175]
	global_load_dwordx4 v[114:117], v[56:57], off
	global_load_dwordx4 v[104:107], v[58:59], off offset:16
	global_load_dwordx4 v[100:103], v[58:59], off offset:512
	s_nop 0
	global_load_dwordx4 v[56:59], v[58:59], off offset:528
	s_mov_b32 s15, 0x80000
	v_lshl_add_u32 v172, v176, 12, v174
	v_add_u32_e32 v173, 0x0, v172
	global_load_dwordx4 v[202:205], v173, s[18:19]
	global_load_dwordx4 v[206:209], v173, s[18:19] offset:16
	global_load_dwordx4 v[210:213], v173, s[18:19] offset:512
	global_load_dwordx4 v[214:217], v173, s[18:19] offset:528
	v_add_u32_e32 v173, 0x10000, v172
	global_load_dwordx4 v[218:221], v173, s[18:19]
	global_load_dwordx4 v[222:225], v173, s[18:19] offset:16
	global_load_dwordx4 v[226:229], v173, s[18:19] offset:512
	global_load_dwordx4 v[230:233], v173, s[18:19] offset:528
	v_add_u32_e32 v173, 0x20000, v172
	global_load_dwordx4 v[146:149], v173, s[18:19]
	global_load_dwordx4 v[150:153], v173, s[18:19] offset:16
	global_load_dwordx4 v[154:157], v173, s[18:19] offset:512
	global_load_dwordx4 v[158:161], v173, s[18:19] offset:528
	v_add_u32_e32 v173, 0x30000, v172
	global_load_dwordx4 v[182:185], v173, s[18:19]
	global_load_dwordx4 v[186:189], v173, s[18:19] offset:16
	global_load_dwordx4 v[190:193], v173, s[18:19] offset:512
	global_load_dwordx4 v[198:201], v173, s[18:19] offset:528
	s_waitcnt vmcnt(12) lgkmcnt(0)
	v_pk_fma_f32 v[142:143], v[142:143], v[114:115], v[202:203]
	v_pk_fma_f32 v[144:145], v[144:145], v[116:117], v[204:205]
	v_pk_fma_f32 v[138:139], v[138:139], v[104:105], v[206:207]
	v_pk_fma_f32 v[140:141], v[140:141], v[106:107], v[208:209]
	v_pk_fma_f32 v[134:135], v[134:135], v[100:101], v[210:211]
	v_pk_fma_f32 v[136:137], v[136:137], v[102:103], v[212:213]
	v_pk_fma_f32 v[130:131], v[130:131], v[56:57], v[214:215]
	v_pk_fma_f32 v[132:133], v[132:133], v[58:59], v[216:217]
	v_add_u32_e32 v173, 0x80000, v172
	global_load_dwordx4 v[202:205], v173, s[18:19]
	global_load_dwordx4 v[206:209], v173, s[18:19] offset:16
	global_load_dwordx4 v[210:213], v173, s[18:19] offset:512
	global_load_dwordx4 v[214:217], v173, s[18:19] offset:528
	v_add_u32_e32 v180, 0x0, v172
	global_store_dwordx4 v180, v[142:145], s[18:19]
	global_store_dwordx4 v180, v[138:141], s[18:19] offset:16
	global_store_dwordx4 v180, v[134:137], s[18:19] offset:512
	global_store_dwordx4 v180, v[130:133], s[18:19] offset:528
	s_waitcnt vmcnt(16)
	v_pk_fma_f32 v[126:127], v[126:127], v[114:115], v[218:219]
	v_pk_fma_f32 v[128:129], v[128:129], v[116:117], v[220:221]
	v_pk_fma_f32 v[122:123], v[122:123], v[104:105], v[222:223]
	v_pk_fma_f32 v[124:125], v[124:125], v[106:107], v[224:225]
	v_pk_fma_f32 v[118:119], v[118:119], v[100:101], v[226:227]
	v_pk_fma_f32 v[120:121], v[120:121], v[102:103], v[228:229]
	v_pk_fma_f32 v[108:109], v[108:109], v[56:57], v[230:231]
	v_pk_fma_f32 v[110:111], v[110:111], v[58:59], v[232:233]
	v_add_u32_e32 v173, 0x90000, v172
	global_load_dwordx4 v[218:221], v173, s[18:19]
	global_load_dwordx4 v[222:225], v173, s[18:19] offset:16
	global_load_dwordx4 v[226:229], v173, s[18:19] offset:512
	global_load_dwordx4 v[230:233], v173, s[18:19] offset:528
	v_add_u32_e32 v180, 0x10000, v172
	global_store_dwordx4 v180, v[126:129], s[18:19]
	global_store_dwordx4 v180, v[122:125], s[18:19] offset:16
	global_store_dwordx4 v180, v[118:121], s[18:19] offset:512
	global_store_dwordx4 v180, v[108:111], s[18:19] offset:528
	s_waitcnt vmcnt(20)
	v_pk_fma_f32 v[96:97], v[96:97], v[114:115], v[146:147]
	v_pk_fma_f32 v[98:99], v[98:99], v[116:117], v[148:149]
	v_pk_fma_f32 v[92:93], v[92:93], v[104:105], v[150:151]
	v_pk_fma_f32 v[94:95], v[94:95], v[106:107], v[152:153]
	v_pk_fma_f32 v[88:89], v[88:89], v[100:101], v[154:155]
	v_pk_fma_f32 v[90:91], v[90:91], v[102:103], v[156:157]
	v_pk_fma_f32 v[84:85], v[84:85], v[56:57], v[158:159]
	v_pk_fma_f32 v[86:87], v[86:87], v[58:59], v[160:161]
	v_add_u32_e32 v173, 0xa0000, v172
	global_load_dwordx4 v[146:149], v173, s[18:19]
	global_load_dwordx4 v[150:153], v173, s[18:19] offset:16
	global_load_dwordx4 v[154:157], v173, s[18:19] offset:512
	global_load_dwordx4 v[158:161], v173, s[18:19] offset:528
	v_add_u32_e32 v180, 0x20000, v172
	global_store_dwordx4 v180, v[96:99], s[18:19]
	global_store_dwordx4 v180, v[92:95], s[18:19] offset:16
	global_store_dwordx4 v180, v[88:91], s[18:19] offset:512
	global_store_dwordx4 v180, v[84:87], s[18:19] offset:528
	s_waitcnt vmcnt(24)
	v_pk_fma_f32 v[80:81], v[80:81], v[114:115], v[182:183]
	v_pk_fma_f32 v[82:83], v[82:83], v[116:117], v[184:185]
	v_pk_fma_f32 v[76:77], v[76:77], v[104:105], v[186:187]
	v_pk_fma_f32 v[78:79], v[78:79], v[106:107], v[188:189]
	v_pk_fma_f32 v[72:73], v[72:73], v[100:101], v[190:191]
	v_pk_fma_f32 v[74:75], v[74:75], v[102:103], v[192:193]
	v_pk_fma_f32 v[68:69], v[68:69], v[56:57], v[198:199]
	v_pk_fma_f32 v[70:71], v[70:71], v[58:59], v[200:201]
	v_add_u32_e32 v173, 0xb0000, v172
	global_load_dwordx4 v[182:185], v173, s[18:19]
	global_load_dwordx4 v[186:189], v173, s[18:19] offset:16
	global_load_dwordx4 v[190:193], v173, s[18:19] offset:512
	global_load_dwordx4 v[198:201], v173, s[18:19] offset:528
	v_add_u32_e32 v180, 0x30000, v172
	global_store_dwordx4 v180, v[80:83], s[18:19]
	global_store_dwordx4 v180, v[76:79], s[18:19] offset:16
	global_store_dwordx4 v180, v[72:75], s[18:19] offset:512
	global_store_dwordx4 v180, v[68:71], s[18:19] offset:528
	s_waitcnt vmcnt(28)
	v_pk_fma_f32 v[64:65], v[64:65], v[114:115], v[202:203]
	v_pk_fma_f32 v[66:67], v[66:67], v[116:117], v[204:205]
	v_pk_fma_f32 v[60:61], v[60:61], v[104:105], v[206:207]
	v_pk_fma_f32 v[62:63], v[62:63], v[106:107], v[208:209]
	v_pk_fma_f32 v[52:53], v[52:53], v[100:101], v[210:211]
	v_pk_fma_f32 v[54:55], v[54:55], v[102:103], v[212:213]
	v_pk_fma_f32 v[48:49], v[48:49], v[56:57], v[214:215]
	v_pk_fma_f32 v[50:51], v[50:51], v[58:59], v[216:217]
	v_add_u32_e32 v180, 0x80000, v172
	global_store_dwordx4 v180, v[64:67], s[18:19]
	global_store_dwordx4 v180, v[60:63], s[18:19] offset:16
	global_store_dwordx4 v180, v[52:55], s[18:19] offset:512
	global_store_dwordx4 v180, v[48:51], s[18:19] offset:528
	s_waitcnt vmcnt(24)
	v_pk_fma_f32 v[44:45], v[44:45], v[114:115], v[218:219]
	v_pk_fma_f32 v[46:47], v[46:47], v[116:117], v[220:221]
	v_pk_fma_f32 v[40:41], v[40:41], v[104:105], v[222:223]
	v_pk_fma_f32 v[42:43], v[42:43], v[106:107], v[224:225]
	v_pk_fma_f32 v[36:37], v[36:37], v[100:101], v[226:227]
	v_pk_fma_f32 v[38:39], v[38:39], v[102:103], v[228:229]
	v_pk_fma_f32 v[32:33], v[32:33], v[56:57], v[230:231]
	v_pk_fma_f32 v[34:35], v[34:35], v[58:59], v[232:233]
	v_add_u32_e32 v180, 0x90000, v172
	global_store_dwordx4 v180, v[44:47], s[18:19]
	global_store_dwordx4 v180, v[40:43], s[18:19] offset:16
	global_store_dwordx4 v180, v[36:39], s[18:19] offset:512
	global_store_dwordx4 v180, v[32:35], s[18:19] offset:528
	s_waitcnt vmcnt(20)
	v_pk_fma_f32 v[28:29], v[28:29], v[114:115], v[146:147]
	v_pk_fma_f32 v[30:31], v[30:31], v[116:117], v[148:149]
	v_pk_fma_f32 v[24:25], v[24:25], v[104:105], v[150:151]
	v_pk_fma_f32 v[26:27], v[26:27], v[106:107], v[152:153]
	v_pk_fma_f32 v[20:21], v[20:21], v[100:101], v[154:155]
	v_pk_fma_f32 v[22:23], v[22:23], v[102:103], v[156:157]
	v_pk_fma_f32 v[16:17], v[16:17], v[56:57], v[158:159]
	v_pk_fma_f32 v[18:19], v[18:19], v[58:59], v[160:161]
	v_add_u32_e32 v180, 0xa0000, v172
	global_store_dwordx4 v180, v[28:31], s[18:19]
	global_store_dwordx4 v180, v[24:27], s[18:19] offset:16
	global_store_dwordx4 v180, v[20:23], s[18:19] offset:512
	global_store_dwordx4 v180, v[16:19], s[18:19] offset:528
	s_waitcnt vmcnt(16)
	v_pk_fma_f32 v[12:13], v[12:13], v[114:115], v[182:183]
	v_pk_fma_f32 v[14:15], v[14:15], v[116:117], v[184:185]
	v_pk_fma_f32 v[8:9], v[8:9], v[104:105], v[186:187]
	v_pk_fma_f32 v[10:11], v[10:11], v[106:107], v[188:189]
	v_pk_fma_f32 v[4:5], v[4:5], v[100:101], v[190:191]
	v_pk_fma_f32 v[6:7], v[6:7], v[102:103], v[192:193]
	v_pk_fma_f32 v[0:1], v[0:1], v[56:57], v[198:199]
	v_pk_fma_f32 v[2:3], v[2:3], v[58:59], v[200:201]
	v_add_u32_e32 v180, 0xb0000, v172
	global_store_dwordx4 v180, v[12:15], s[18:19]
	global_store_dwordx4 v180, v[8:11], s[18:19] offset:16
	global_store_dwordx4 v180, v[4:7], s[18:19] offset:512
	global_store_dwordx4 v180, v[0:3], s[18:19] offset:528
	s_nop 1
	s_mov_b64 s[18:19], -1
	s_mov_b32 s15, 0xb0000
	s_andn2_b64 vcc, exec, s[42:43]
	s_cbranch_vccnz .LBB0_1749
	s_andn2_b64 vcc, exec, s[10:11]
	s_cbranch_vccnz .LBB0_1748
	s_barrier
	s_branch .LBB0_1748
